# attention QK blocks: K fragment reads for d0=2,3 issued behind the MFMA that last used the fragment, counted lgkmcnt waits instead of lgkmcnt(0) after fresh reads
# speedup vs baseline: 1.0106x; 1.0081x over previous
.LBB0_1031:
	s_lshl_b32 s0, s75, 13
	s_add_i32 s77, s0, 0
	s_setprio 1
	v_add_u32_e32 v112, s77, v189
	v_add_u32_e32 v68, v112, v191
	ds_read_b128 v[64:67], v68 offset:49152
	ds_read_b128 v[68:71], v68 offset:53248
	v_add_u32_e32 v113, v112, v192
	ds_read_b128 v[220:223], v113 offset:49152
	ds_read_b128 v[224:227], v113 offset:53248
	v_add_u32_e32 v113, v112, v193
	s_waitcnt lgkmcnt(2)
	v_mfma_f32_32x32x16_bf16 v[80:95], v[64:67], v[108:111], 0
	v_add_u32_e32 v112, v112, v194
	v_mfma_f32_32x32x16_bf16 v[64:79], v[68:71], v[108:111], 0
	s_waitcnt lgkmcnt(0)
	v_mfma_f32_32x32x16_bf16 v[80:95], v[220:223], v[104:107], v[80:95]
	ds_read_b128 v[220:223], v113 offset:49152
	v_mfma_f32_32x32x16_bf16 v[64:79], v[224:227], v[104:107], v[64:79]
	ds_read_b128 v[224:227], v113 offset:53248
	s_waitcnt lgkmcnt(1)
	v_mfma_f32_32x32x16_bf16 v[80:95], v[220:223], v[100:103], v[80:95]
	ds_read_b128 v[220:223], v112 offset:49152
	s_waitcnt lgkmcnt(1)
	v_mfma_f32_32x32x16_bf16 v[64:79], v[224:227], v[100:103], v[64:79]
	ds_read_b128 v[224:227], v112 offset:53248
	s_waitcnt lgkmcnt(1)
	v_mfma_f32_32x32x16_bf16 v[80:95], v[220:223], v[96:99], v[80:95]
	s_waitcnt lgkmcnt(0)
	v_mfma_f32_32x32x16_bf16 v[64:79], v[224:227], v[96:99], v[64:79]
	s_setprio 0
	v_exp_f32_e32 v174, v174
	v_exp_f32_e32 v175, v175
	v_add_f32_e32 v112, v115, v174
	v_add_f32_e32 v113, v124, v175
	v_exp_f32_e32 v172, v172
	v_add_f32_e32 v112, v112, v125
	v_add_f32_e32 v113, v113, v126
	v_exp_f32_e32 v173, v173
	v_add_f32_e32 v112, v112, v172
	v_add_f32_e32 v113, v113, v173
	v_exp_f32_e32 v170, v170
	v_add_f32_e32 v112, v112, v127
	v_add_f32_e32 v113, v113, v176
	v_exp_f32_e32 v171, v171
	v_add_f32_e32 v112, v112, v170
	v_add_f32_e32 v113, v113, v171
	v_exp_f32_e32 v168, v168
	v_add_f32_e32 v112, v112, v177
	v_add_f32_e32 v113, v113, v178
	v_exp_f32_e32 v169, v169
	v_add_f32_e32 v112, v112, v168
	v_add_f32_e32 v113, v113, v169
	v_exp_f32_e32 v166, v166
	v_add_f32_e32 v112, v112, v116
	v_add_f32_e32 v113, v113, v117
	v_exp_f32_e32 v167, v167
	v_add_f32_e32 v112, v112, v166
	v_add_f32_e32 v113, v113, v167
	v_exp_f32_e32 v164, v164
	v_add_f32_e32 v112, v112, v118
	v_add_f32_e32 v113, v113, v119
	v_exp_f32_e32 v165, v165
	v_add_f32_e32 v112, v112, v164
	v_add_f32_e32 v113, v113, v165
	v_exp_f32_e32 v162, v162
	v_add_f32_e32 v112, v112, v120
	v_add_f32_e32 v113, v113, v121
	v_exp_f32_e32 v163, v163
	v_exp_f32_e32 v160, v160
	v_exp_f32_e32 v161, v161
	v_add_f32_e32 v112, v112, v162
	v_add_f32_e32 v113, v113, v163
	s_nop 0
	v_add_f32_e32 v112, v112, v122
	v_add_f32_e32 v113, v113, v123
	s_nop 0
	v_add_f32_e32 v112, v112, v160
	v_add_f32_e32 v113, v113, v161
	s_nop 0
	v_add_f32_e32 v219, v112, v113
	v_cvt_pk_bf16_f32 v112, v115, v124
	v_cvt_pk_bf16_f32 v113, v125, v126
	v_cvt_pk_bf16_f32 v114, v127, v176
	v_cvt_pk_bf16_f32 v115, v177, v178
	v_cvt_pk_bf16_f32 v116, v116, v117
	s_nop 0
	v_mov_b32_e32 v220, v219
	s_nop 1
	v_permlane32_swap_b32_e32 v219, v220
	v_cvt_pk_bf16_f32 v117, v118, v119
	v_cvt_pk_bf16_f32 v118, v120, v121
	v_cvt_pk_bf16_f32 v119, v122, v123
	v_cvt_pk_bf16_f32 v120, v174, v175
	v_cvt_pk_bf16_f32 v121, v172, v173
	v_cvt_pk_bf16_f32 v122, v170, v171
	v_cvt_pk_bf16_f32 v123, v168, v169
	v_cvt_pk_bf16_f32 v124, v166, v167
	v_cvt_pk_bf16_f32 v125, v164, v165
	v_cvt_pk_bf16_f32 v126, v162, v163
	v_cvt_pk_bf16_f32 v127, v160, v161
	v_permlane32_swap_b32_e32 v112, v114
	v_permlane32_swap_b32_e32 v113, v115
	v_permlane32_swap_b32_e32 v116, v118
	v_permlane32_swap_b32_e32 v117, v119
	v_permlane32_swap_b32_e32 v120, v122
	v_permlane32_swap_b32_e32 v121, v123
	v_permlane32_swap_b32_e32 v124, v126
	v_permlane32_swap_b32_e32 v125, v127
	s_lshl_b32 s0, s76, 14
	v_add_u32_e32 v176, s0, v187
	ds_read_b64_tr_b16 v[160:161], v176 offset:0
	ds_read_b64_tr_b16 v[162:163], v176 offset:0x800
	ds_read_b64_tr_b16 v[164:165], v176 offset:0x1000
	ds_read_b64_tr_b16 v[166:167], v176 offset:0x1800
	ds_read_b64_tr_b16 v[168:169], v176 offset:0x2000
	ds_read_b64_tr_b16 v[170:171], v176 offset:0x2800
	ds_read_b64_tr_b16 v[172:173], v176 offset:0x3000
	ds_read_b64_tr_b16 v[174:175], v176 offset:0x3800
	s_setprio 1
	s_waitcnt lgkmcnt(6)
	v_mfma_f32_32x32x16_bf16 v[48:63], v[112:115], v[160:163], v[48:63]
	s_waitcnt lgkmcnt(4)
	v_mfma_f32_32x32x16_bf16 v[48:63], v[116:119], v[164:167], v[48:63]
	s_waitcnt lgkmcnt(2)
	v_mfma_f32_32x32x16_bf16 v[48:63], v[120:123], v[168:171], v[48:63]
	s_waitcnt lgkmcnt(0)
	v_mfma_f32_32x32x16_bf16 v[48:63], v[124:127], v[172:175], v[48:63]
	s_setprio 0
	v_max3_f32 v160, v80, v81, v82
	v_max3_f32 v161, v64, v65, v66
	v_max_f32_e32 v162, v79, v79
	v_max3_f32 v160, v160, v83, v84
	v_max3_f32 v161, v161, v67, v68
	v_max_f32_e32 v163, v95, v95
	v_max3_f32 v160, v160, v85, v86
	v_max3_f32 v161, v161, v69, v70
	v_max_f32_e32 v162, v163, v162
	v_max3_f32 v160, v160, v87, v88
	v_max3_f32 v161, v161, v71, v72
	s_nop 0
	v_max3_f32 v160, v160, v89, v90
	v_max3_f32 v161, v161, v73, v74
	s_nop 0
	v_max3_f32 v160, v160, v91, v92
	v_max3_f32 v161, v161, v75, v76
	s_nop 0
	v_max3_f32 v160, v160, v93, v94
	v_max3_f32 v161, v161, v77, v78
	s_nop 0
	v_max3_f32 v160, v160, v161, v162
	s_nop 0
	v_mov_b32_e32 v161, v160
	s_nop 1
	v_permlane32_swap_b32_e32 v160, v161
	v_max_f32_e32 v161, v161, v161
	v_max_f32_e32 v160, v160, v160
	v_max_f32_e32 v177, v160, v161
	ds_read_b64_tr_b16 v[160:161], v176 offset:0x200
	ds_read_b64_tr_b16 v[162:163], v176 offset:0xa00
	ds_read_b64_tr_b16 v[164:165], v176 offset:0x1200
	ds_read_b64_tr_b16 v[166:167], v176 offset:0x1a00
	ds_read_b64_tr_b16 v[168:169], v176 offset:0x2200
	ds_read_b64_tr_b16 v[170:171], v176 offset:0x2a00
	ds_read_b64_tr_b16 v[172:173], v176 offset:0x3200
	ds_read_b64_tr_b16 v[174:175], v176 offset:0x3a00
	s_setprio 1
	s_waitcnt lgkmcnt(6)
	v_mfma_f32_32x32x16_bf16 v[32:47], v[112:115], v[160:163], v[32:47]
	s_waitcnt lgkmcnt(4)
	v_mfma_f32_32x32x16_bf16 v[32:47], v[116:119], v[164:167], v[32:47]
	s_waitcnt lgkmcnt(2)
	v_mfma_f32_32x32x16_bf16 v[32:47], v[120:123], v[168:171], v[32:47]
	s_waitcnt lgkmcnt(0)
	v_mfma_f32_32x32x16_bf16 v[32:47], v[124:127], v[172:175], v[32:47]
	s_setprio 0
	v_sub_f32_e32 v160, v177, v218
	v_cmp_ge_f32_e32 vcc, s71, v160
	v_max_f32_e32 v160, v218, v218
	v_max_f32_e32 v160, v160, v177
	v_sub_f32_e32 v161, v218, v160
	v_mul_f32_e32 v161, 0x3e38aa3b, v161
	v_exp_f32_e32 v161, v161
	s_cmp_eq_u64 vcc, exec
	s_cselect_b64 vcc, -1, 0
	v_cndmask_b32_e32 v222, v160, v218, vcc
	v_cndmask_b32_e64 v221, v161, 1.0, vcc
	v_mul_f32_e32 v175, 0xbe38aa3b, v222
	v_fma_f32 v80, v80, v197, v175
	v_fma_f32 v81, v81, v197, v175
	v_fma_f32 v82, v82, v197, v175
	v_fma_f32 v83, v83, v197, v175
	v_fma_f32 v84, v84, v197, v175
	v_fma_f32 v85, v85, v197, v175
	v_fma_f32 v86, v86, v197, v175
	v_fma_f32 v87, v87, v197, v175
	v_fma_f32 v88, v88, v197, v175
	v_fma_f32 v89, v89, v197, v175
	v_fma_f32 v90, v90, v197, v175
	v_fma_f32 v91, v91, v197, v175
	v_fma_f32 v92, v92, v197, v175
	v_fma_f32 v93, v93, v197, v175
	v_fma_f32 v94, v94, v197, v175
	v_fma_f32 v95, v95, v197, v175
	v_fma_f32 v160, v64, v197, v175
	v_fma_f32 v161, v65, v197, v175
	v_fma_f32 v162, v66, v197, v175
	v_fma_f32 v163, v67, v197, v175
	v_fma_f32 v164, v68, v197, v175
	v_fma_f32 v165, v69, v197, v175
	v_fma_f32 v166, v70, v197, v175
	v_fma_f32 v167, v71, v197, v175
	v_fma_f32 v168, v72, v197, v175
	v_fma_f32 v169, v73, v197, v175
	v_fma_f32 v170, v74, v197, v175
	v_fma_f32 v171, v75, v197, v175
	v_fma_f32 v172, v76, v197, v175
	v_fma_f32 v173, v77, v197, v175
	v_fma_f32 v174, v78, v197, v175
	v_fma_f32 v175, v79, v197, v175
	ds_read_b64_tr_b16 v[64:65], v176 offset:0x400
	ds_read_b64_tr_b16 v[66:67], v176 offset:0xc00
	ds_read_b64_tr_b16 v[68:69], v176 offset:0x1400
	ds_read_b64_tr_b16 v[70:71], v176 offset:0x1c00
	ds_read_b64_tr_b16 v[72:73], v176 offset:0x2400
	ds_read_b64_tr_b16 v[74:75], v176 offset:0x2c00
	ds_read_b64_tr_b16 v[76:77], v176 offset:0x3400
	ds_read_b64_tr_b16 v[78:79], v176 offset:0x3c00
	s_setprio 1
	s_waitcnt lgkmcnt(6)
	v_mfma_f32_32x32x16_bf16 v[16:31], v[112:115], v[64:67], v[16:31]
	ds_read_b64_tr_b16 v[64:65], v176 offset:0x600
	ds_read_b64_tr_b16 v[66:67], v176 offset:0xe00
	s_waitcnt lgkmcnt(6)
	v_mfma_f32_32x32x16_bf16 v[16:31], v[116:119], v[68:71], v[16:31]
	ds_read_b64_tr_b16 v[68:69], v176 offset:0x1600
	ds_read_b64_tr_b16 v[70:71], v176 offset:0x1e00
	s_waitcnt lgkmcnt(6)
	v_mfma_f32_32x32x16_bf16 v[16:31], v[120:123], v[72:75], v[16:31]
	ds_read_b64_tr_b16 v[72:73], v176 offset:0x2600
	ds_read_b64_tr_b16 v[74:75], v176 offset:0x2e00
	s_waitcnt lgkmcnt(6)
	v_mfma_f32_32x32x16_bf16 v[16:31], v[124:127], v[76:79], v[16:31]
	ds_read_b64_tr_b16 v[76:77], v176 offset:0x3600
	ds_read_b64_tr_b16 v[78:79], v176 offset:0x3e00
	s_setprio 0
	s_setprio 0
	s_lshl_b32 s1, s76, 13
	v_lshl_add_u64 v[176:177], s[46:47], 0, v[154:155]
	s_mov_b64 s[48:49], 0x14210800
	s_add_i32 s1, s51, s1
	s_waitcnt vmcnt(0) lgkmcnt(0)
	s_barrier
	s_setprio 1
	v_mfma_f32_32x32x16_bf16 v[0:15], v[112:115], v[64:67], v[0:15]
	v_lshl_add_u64 v[226:227], v[176:177], 0, s[48:49]
	s_add_i32 m0, s1, 0xc000
	v_lshl_add_u64 v[178:179], s[46:47], 0, v[156:157]
	s_add_i32 s0, s51, s0
	global_load_lds_dwordx4 v[226:227], off
	v_mfma_f32_32x32x16_bf16 v[0:15], v[116:119], v[68:71], v[0:15]
	v_lshl_add_u64 v[226:227], v[178:179], 0, s[10:11]
	s_mov_b32 m0, s0
	v_lshl_add_u64 v[180:181], s[46:47], 0, v[158:159]
	global_load_lds_dwordx4 v[226:227], off
	v_mfma_f32_32x32x16_bf16 v[0:15], v[120:123], v[72:75], v[0:15]
	v_lshl_add_u64 v[226:227], v[180:181], 0, s[10:11]
	s_add_i32 m0, s0, 0x2000
	v_cmp_gt_f32_e32 vcc, 1.0, v221
	global_load_lds_dwordx4 v[226:227], off
	v_mfma_f32_32x32x16_bf16 v[0:15], v[124:127], v[76:79], v[0:15]
	s_setprio 0
	s_cbranch_vccz .LBB0_1035
	s_and_saveexec_b64 s[0:1], s[4:5]
	ds_write_b32 v215, v221 offset:128
	s_or_b64 exec, exec, s[0:1]
	s_waitcnt lgkmcnt(0)
	v_add_u32_e32 v76, s50, v188
	ds_read_b128 v[64:67], v76 offset:224
	ds_read_b128 v[68:71], v76 offset:192
	ds_read_b128 v[72:75], v76 offset:160
	ds_read_b128 v[76:79], v76 offset:128
	s_waitcnt lgkmcnt(0)
	v_pk_mul_f32 v[60:61], v[60:61], v[64:65]
	v_pk_mul_f32 v[56:57], v[56:57], v[68:69]
	v_pk_mul_f32 v[52:53], v[52:53], v[72:73]
	v_pk_mul_f32 v[62:63], v[62:63], v[66:67]
	v_pk_mul_f32 v[58:59], v[58:59], v[70:71]
	v_pk_mul_f32 v[54:55], v[54:55], v[74:75]
	v_pk_mul_f32 v[50:51], v[50:51], v[78:79]
	v_pk_mul_f32 v[48:49], v[48:49], v[76:77]
	v_pk_mul_f32 v[44:45], v[44:45], v[64:65]
	v_pk_mul_f32 v[40:41], v[40:41], v[68:69]
	v_pk_mul_f32 v[36:37], v[36:37], v[72:73]
	v_pk_mul_f32 v[46:47], v[46:47], v[66:67]
	v_pk_mul_f32 v[42:43], v[42:43], v[70:71]
	v_pk_mul_f32 v[38:39], v[38:39], v[74:75]
	v_pk_mul_f32 v[34:35], v[34:35], v[78:79]
	v_pk_mul_f32 v[32:33], v[32:33], v[76:77]
	v_pk_mul_f32 v[28:29], v[28:29], v[64:65]
	v_pk_mul_f32 v[24:25], v[24:25], v[68:69]
	v_pk_mul_f32 v[20:21], v[20:21], v[72:73]
	v_pk_mul_f32 v[30:31], v[30:31], v[66:67]
	v_pk_mul_f32 v[26:27], v[26:27], v[70:71]
	v_pk_mul_f32 v[22:23], v[22:23], v[74:75]
	v_pk_mul_f32 v[18:19], v[18:19], v[78:79]
	v_pk_mul_f32 v[16:17], v[16:17], v[76:77]
	v_pk_mul_f32 v[12:13], v[12:13], v[64:65]
	v_pk_mul_f32 v[8:9], v[8:9], v[68:69]
	v_pk_mul_f32 v[4:5], v[4:5], v[72:73]
	v_pk_mul_f32 v[14:15], v[14:15], v[66:67]
	v_pk_mul_f32 v[10:11], v[10:11], v[70:71]
	v_pk_mul_f32 v[6:7], v[6:7], v[74:75]
	v_pk_mul_f32 v[2:3], v[2:3], v[78:79]
	v_pk_mul_f32 v[0:1], v[0:1], v[76:77]
.LBB0_1035:
	v_exp_f32_e32 v218, v88
	v_exp_f32_e32 v225, v89
	s_add_i32 s0, s75, 1
	s_cmp_lg_u32 s75, 2
	s_cselect_b32 s76, s0, 0
	v_exp_f32_e32 v120, v80
	v_exp_f32_e32 v121, v81
	v_exp_f32_e32 v122, v82
	v_exp_f32_e32 v123, v83
	v_exp_f32_e32 v124, v84
	v_exp_f32_e32 v125, v85
	v_exp_f32_e32 v126, v86
	v_exp_f32_e32 v127, v87
	v_exp_f32_e32 v226, v90
	v_exp_f32_e32 v227, v91
	v_exp_f32_e32 v228, v92
	v_exp_f32_e32 v229, v93
	v_exp_f32_e32 v230, v94
	v_exp_f32_e32 v231, v95
	s_setprio 1
	v_lshl_add_u32 v223, s76, 13, v190
	v_add_u32_e32 v68, v223, v191
	ds_read_b128 v[64:67], v68 offset:49152
	ds_read_b128 v[68:71], v68 offset:53248
	v_add_u32_e32 v116, v223, v192
	ds_read_b128 v[112:115], v116 offset:49152
	ds_read_b128 v[116:119], v116 offset:53248
	s_waitcnt lgkmcnt(2)
	v_mfma_f32_32x32x16_bf16 v[80:95], v[64:67], v[108:111], 0
	v_mfma_f32_32x32x16_bf16 v[64:79], v[68:71], v[108:111], 0
	s_waitcnt lgkmcnt(0)
	v_mfma_f32_32x32x16_bf16 v[80:95], v[112:115], v[104:107], v[80:95]
	v_add_u32_e32 v112, v223, v193
	ds_read_b128 v[112:115], v112 offset:49152
	v_mfma_f32_32x32x16_bf16 v[64:79], v[116:119], v[104:107], v[64:79]
	v_add_u32_e32 v116, v223, v193
	ds_read_b128 v[116:119], v116 offset:53248
	s_waitcnt lgkmcnt(1)
	v_mfma_f32_32x32x16_bf16 v[80:95], v[112:115], v[100:103], v[80:95]
	v_add_u32_e32 v112, v223, v194
	ds_read_b128 v[112:115], v112 offset:49152
	s_waitcnt lgkmcnt(1)
	v_mfma_f32_32x32x16_bf16 v[64:79], v[116:119], v[100:103], v[64:79]
	v_add_u32_e32 v116, v223, v194
	ds_read_b128 v[116:119], v116 offset:53248
	s_waitcnt lgkmcnt(1)
	v_mfma_f32_32x32x16_bf16 v[80:95], v[112:115], v[96:99], v[80:95]
	s_waitcnt lgkmcnt(0)
	v_mfma_f32_32x32x16_bf16 v[64:79], v[116:119], v[96:99], v[64:79]
	s_setprio 0
	v_exp_f32_e32 v160, v160
	v_exp_f32_e32 v161, v161
	v_add_f32_e32 v112, v120, v160
	v_add_f32_e32 v113, v121, v161
	v_exp_f32_e32 v162, v162
	v_add_f32_e32 v112, v112, v122
	v_add_f32_e32 v113, v113, v123
	v_exp_f32_e32 v163, v163
	v_add_f32_e32 v112, v112, v162
	v_add_f32_e32 v113, v113, v163
	v_exp_f32_e32 v164, v164
	v_add_f32_e32 v112, v112, v124
	v_add_f32_e32 v113, v113, v125
	v_exp_f32_e32 v165, v165
	v_add_f32_e32 v112, v112, v164
	v_add_f32_e32 v113, v113, v165
	v_exp_f32_e32 v166, v166
	v_add_f32_e32 v112, v112, v126
	v_add_f32_e32 v113, v113, v127
	v_exp_f32_e32 v167, v167
	v_add_f32_e32 v112, v112, v166
	v_add_f32_e32 v113, v113, v167
	v_exp_f32_e32 v168, v168
	v_add_f32_e32 v112, v112, v218
	v_add_f32_e32 v113, v113, v225
	v_exp_f32_e32 v169, v169
	v_add_f32_e32 v112, v112, v168
	v_add_f32_e32 v113, v113, v169
	v_exp_f32_e32 v170, v170
	v_add_f32_e32 v112, v112, v226
	v_add_f32_e32 v113, v113, v227
	v_exp_f32_e32 v171, v171
	v_add_f32_e32 v112, v112, v170
	v_add_f32_e32 v113, v113, v171
	v_exp_f32_e32 v172, v172
	v_add_f32_e32 v112, v112, v228
	v_add_f32_e32 v113, v113, v229
	v_exp_f32_e32 v173, v173
	v_exp_f32_e32 v174, v174
	v_exp_f32_e32 v175, v175
	v_add_f32_e32 v112, v112, v172
	v_add_f32_e32 v113, v113, v173
	s_nop 0
	v_add_f32_e32 v112, v112, v230
	v_add_f32_e32 v113, v113, v231
	s_nop 0
	v_add_f32_e32 v112, v112, v174
	v_add_f32_e32 v113, v113, v175
	s_nop 0
	v_add_f32_e32 v223, v112, v113
	v_cvt_pk_bf16_f32 v112, v120, v121
	v_cvt_pk_bf16_f32 v113, v122, v123
	v_cvt_pk_bf16_f32 v114, v124, v125
	v_cvt_pk_bf16_f32 v115, v126, v127
	v_cvt_pk_bf16_f32 v116, v218, v225
	s_nop 0
	v_mov_b32_e32 v224, v223
	s_nop 1
	v_permlane32_swap_b32_e32 v223, v224
	v_cvt_pk_bf16_f32 v117, v226, v227
	v_cvt_pk_bf16_f32 v118, v228, v229
	v_cvt_pk_bf16_f32 v119, v230, v231
	v_cvt_pk_bf16_f32 v120, v160, v161
	v_cvt_pk_bf16_f32 v121, v162, v163
	v_cvt_pk_bf16_f32 v122, v164, v165
	v_cvt_pk_bf16_f32 v123, v166, v167
	v_cvt_pk_bf16_f32 v124, v168, v169
	v_cvt_pk_bf16_f32 v125, v170, v171
	v_cvt_pk_bf16_f32 v126, v172, v173
	v_cvt_pk_bf16_f32 v127, v174, v175
	v_permlane32_swap_b32_e32 v112, v114
	v_permlane32_swap_b32_e32 v113, v115
	v_permlane32_swap_b32_e32 v116, v118
	v_permlane32_swap_b32_e32 v117, v119
	v_permlane32_swap_b32_e32 v120, v122
	v_permlane32_swap_b32_e32 v121, v123
	v_permlane32_swap_b32_e32 v124, v126
	v_permlane32_swap_b32_e32 v125, v127
	s_lshl_b32 s75, s75, 14
	v_add_u32_e32 v226, s75, v187
	ds_read_b64_tr_b16 v[160:161], v226 offset:0
	ds_read_b64_tr_b16 v[162:163], v226 offset:0x800
	ds_read_b64_tr_b16 v[164:165], v226 offset:0x1000
	ds_read_b64_tr_b16 v[166:167], v226 offset:0x1800
	ds_read_b64_tr_b16 v[168:169], v226 offset:0x2000
	ds_read_b64_tr_b16 v[170:171], v226 offset:0x2800
	ds_read_b64_tr_b16 v[172:173], v226 offset:0x3000
	ds_read_b64_tr_b16 v[174:175], v226 offset:0x3800
	s_setprio 1
	s_waitcnt lgkmcnt(6)
	v_mfma_f32_32x32x16_bf16 v[48:63], v[112:115], v[160:163], v[48:63]
	s_waitcnt lgkmcnt(4)
	v_mfma_f32_32x32x16_bf16 v[48:63], v[116:119], v[164:167], v[48:63]
	s_waitcnt lgkmcnt(2)
	v_mfma_f32_32x32x16_bf16 v[48:63], v[120:123], v[168:171], v[48:63]
	s_waitcnt lgkmcnt(0)
	v_mfma_f32_32x32x16_bf16 v[48:63], v[124:127], v[172:175], v[48:63]
	s_setprio 0
	v_max3_f32 v160, v80, v81, v82
	v_max3_f32 v161, v64, v65, v66
	v_max_f32_e32 v162, v79, v79
	v_max3_f32 v160, v160, v83, v84
	v_max3_f32 v161, v161, v67, v68
	v_max_f32_e32 v163, v95, v95
	v_max3_f32 v160, v160, v85, v86
	v_max3_f32 v161, v161, v69, v70
	v_max_f32_e32 v162, v163, v162
	v_max3_f32 v160, v160, v87, v88
	v_max3_f32 v161, v161, v71, v72
	s_nop 0
	v_max3_f32 v160, v160, v89, v90
	v_max3_f32 v161, v161, v73, v74
	s_nop 0
	v_max3_f32 v160, v160, v91, v92
	v_max3_f32 v161, v161, v75, v76
	s_nop 0
	v_max3_f32 v160, v160, v93, v94
	v_max3_f32 v161, v161, v77, v78
	s_nop 0
	v_max3_f32 v160, v160, v161, v162
	s_nop 0
	v_mov_b32_e32 v161, v160
	s_nop 1
	v_permlane32_swap_b32_e32 v160, v161
	v_max_f32_e32 v161, v161, v161
	v_max_f32_e32 v160, v160, v160
	v_max_f32_e32 v218, v160, v161
	ds_read_b64_tr_b16 v[160:161], v226 offset:0x200
	ds_read_b64_tr_b16 v[162:163], v226 offset:0xa00
	ds_read_b64_tr_b16 v[164:165], v226 offset:0x1200
	ds_read_b64_tr_b16 v[166:167], v226 offset:0x1a00
	ds_read_b64_tr_b16 v[168:169], v226 offset:0x2200
	ds_read_b64_tr_b16 v[170:171], v226 offset:0x2a00
	ds_read_b64_tr_b16 v[172:173], v226 offset:0x3200
	ds_read_b64_tr_b16 v[174:175], v226 offset:0x3a00
	s_setprio 1
	s_waitcnt lgkmcnt(6)
	v_mfma_f32_32x32x16_bf16 v[32:47], v[112:115], v[160:163], v[32:47]
	s_waitcnt lgkmcnt(4)
	v_mfma_f32_32x32x16_bf16 v[32:47], v[116:119], v[164:167], v[32:47]
	s_waitcnt lgkmcnt(2)
	v_mfma_f32_32x32x16_bf16 v[32:47], v[120:123], v[168:171], v[32:47]
	s_waitcnt lgkmcnt(0)
	v_mfma_f32_32x32x16_bf16 v[32:47], v[124:127], v[172:175], v[32:47]
	s_setprio 0
	v_sub_f32_e32 v160, v218, v222
	v_cmp_ge_f32_e32 vcc, s71, v160
	s_cmp_eq_u64 vcc, exec
	v_max_f32_e32 v160, v222, v222
	v_max_f32_e32 v225, v160, v218
	s_cselect_b64 s[0:1], -1, 0
	v_cndmask_b32_e64 v218, v225, v222, s[0:1]
	v_mul_f32_e32 v161, 0xbe38aa3b, v218
	v_fma_f32 v80, v80, v197, v161
	v_fma_f32 v81, v81, v197, v161
	v_fma_f32 v82, v82, v197, v161
	v_fma_f32 v83, v83, v197, v161
	v_fma_f32 v84, v84, v197, v161
	v_fma_f32 v85, v85, v197, v161
	v_fma_f32 v86, v86, v197, v161
	v_fma_f32 v87, v87, v197, v161
	v_fma_f32 v88, v88, v197, v161
	v_fma_f32 v89, v89, v197, v161
	v_fma_f32 v90, v90, v197, v161
	v_fma_f32 v91, v91, v197, v161
	v_fma_f32 v92, v92, v197, v161
	v_fma_f32 v93, v93, v197, v161
	v_fma_f32 v94, v94, v197, v161
	v_fma_f32 v95, v95, v197, v161
	v_fma_f32 v174, v64, v197, v161
	v_fma_f32 v175, v65, v197, v161
	v_fma_f32 v172, v66, v197, v161
	v_fma_f32 v173, v67, v197, v161
	v_fma_f32 v170, v68, v197, v161
	v_fma_f32 v171, v69, v197, v161
	v_fma_f32 v168, v70, v197, v161
	v_fma_f32 v169, v71, v197, v161
	v_fma_f32 v166, v72, v197, v161
	v_fma_f32 v167, v73, v197, v161
	v_fma_f32 v164, v74, v197, v161
	v_fma_f32 v165, v75, v197, v161
	v_fma_f32 v162, v76, v197, v161
	v_fma_f32 v163, v77, v197, v161
	v_fma_f32 v160, v78, v197, v161
	v_fma_f32 v161, v79, v197, v161
	ds_read_b64_tr_b16 v[64:65], v226 offset:0x400
	ds_read_b64_tr_b16 v[66:67], v226 offset:0xc00
	ds_read_b64_tr_b16 v[68:69], v226 offset:0x1400
	ds_read_b64_tr_b16 v[70:71], v226 offset:0x1c00
	ds_read_b64_tr_b16 v[72:73], v226 offset:0x2400
	ds_read_b64_tr_b16 v[74:75], v226 offset:0x2c00
	ds_read_b64_tr_b16 v[76:77], v226 offset:0x3400
	ds_read_b64_tr_b16 v[78:79], v226 offset:0x3c00
	s_setprio 1
	s_waitcnt lgkmcnt(6)
	v_mfma_f32_32x32x16_bf16 v[16:31], v[112:115], v[64:67], v[16:31]
	ds_read_b64_tr_b16 v[64:65], v226 offset:0x600
	ds_read_b64_tr_b16 v[66:67], v226 offset:0xe00
	s_waitcnt lgkmcnt(6)
	v_mfma_f32_32x32x16_bf16 v[16:31], v[116:119], v[68:71], v[16:31]
	ds_read_b64_tr_b16 v[68:69], v226 offset:0x1600
	ds_read_b64_tr_b16 v[70:71], v226 offset:0x1e00
	s_waitcnt lgkmcnt(6)
	v_mfma_f32_32x32x16_bf16 v[16:31], v[120:123], v[72:75], v[16:31]
	ds_read_b64_tr_b16 v[72:73], v226 offset:0x2600
	ds_read_b64_tr_b16 v[74:75], v226 offset:0x2e00
	s_waitcnt lgkmcnt(6)
	v_mfma_f32_32x32x16_bf16 v[16:31], v[124:127], v[76:79], v[16:31]
	ds_read_b64_tr_b16 v[76:77], v226 offset:0x3600
	ds_read_b64_tr_b16 v[78:79], v226 offset:0x3e00
	s_setprio 0
	s_setprio 0
	s_waitcnt vmcnt(0) lgkmcnt(0)
	s_barrier
	s_cmp_gt_u32 s74, 28
	s_cselect_b64 s[48:49], -1, 0
	s_and_b64 vcc, exec, s[48:49]
	s_cbranch_vccnz .Lpv3_skip_a
	s_add_i32 s77, s77, s33
	s_setprio 1
	v_mfma_f32_32x32x16_bf16 v[0:15], v[112:115], v[64:67], v[0:15]
	s_add_i32 m0, s77, 0xc000
	s_add_i32 s75, s51, s75
	v_lshl_add_u64 v[64:65], v[176:177], 0, s[14:15]
	global_load_lds_dwordx4 v[64:65], off
	v_mfma_f32_32x32x16_bf16 v[0:15], v[116:119], v[68:71], v[0:15]
	v_lshl_add_u64 v[64:65], v[178:179], 0, s[34:35]
	s_mov_b32 m0, s75
	s_nop 0
	global_load_lds_dwordx4 v[64:65], off
	v_mfma_f32_32x32x16_bf16 v[0:15], v[120:123], v[72:75], v[0:15]
	v_lshl_add_u64 v[64:65], v[180:181], 0, s[34:35]
	s_add_i32 m0, s75, 0x2000
	s_nop 0
	global_load_lds_dwordx4 v[64:65], off
	v_mfma_f32_32x32x16_bf16 v[0:15], v[124:127], v[76:79], v[0:15]
	s_setprio 0
	s_branch .LBB0_1037

.LBB0_1050:
	s_lshl_b32 s0, s76, 13
	s_add_i32 s40, s0, 0
	s_setprio 1
	v_add_u32_e32 v112, s40, v189
	v_add_u32_e32 v68, v112, v191
	ds_read_b128 v[64:67], v68 offset:49152
	ds_read_b128 v[68:71], v68 offset:53248
	v_add_u32_e32 v113, v112, v192
	ds_read_b128 v[228:231], v113 offset:49152
	ds_read_b128 v[232:235], v113 offset:53248
	v_add_u32_e32 v113, v112, v193
	s_waitcnt lgkmcnt(2)
	v_mfma_f32_32x32x16_bf16 v[80:95], v[64:67], v[108:111], 0
	v_add_u32_e32 v112, v112, v194
	v_mfma_f32_32x32x16_bf16 v[64:79], v[68:71], v[108:111], 0
	s_waitcnt lgkmcnt(0)
	v_mfma_f32_32x32x16_bf16 v[80:95], v[228:231], v[104:107], v[80:95]
	ds_read_b128 v[228:231], v113 offset:49152
	v_mfma_f32_32x32x16_bf16 v[64:79], v[232:235], v[104:107], v[64:79]
	ds_read_b128 v[232:235], v113 offset:53248
	s_waitcnt lgkmcnt(1)
	v_mfma_f32_32x32x16_bf16 v[80:95], v[228:231], v[100:103], v[80:95]
	ds_read_b128 v[228:231], v112 offset:49152
	s_waitcnt lgkmcnt(1)
	v_mfma_f32_32x32x16_bf16 v[64:79], v[232:235], v[100:103], v[64:79]
	ds_read_b128 v[232:235], v112 offset:53248
	s_waitcnt lgkmcnt(1)
	v_mfma_f32_32x32x16_bf16 v[80:95], v[228:231], v[96:99], v[80:95]
	s_waitcnt lgkmcnt(0)
	v_mfma_f32_32x32x16_bf16 v[64:79], v[232:235], v[96:99], v[64:79]
	s_setprio 0
	v_exp_f32_e32 v163, v180
	v_exp_f32_e32 v164, v181
	v_add_f32_e32 v112, v115, v163
	v_add_f32_e32 v113, v124, v164
	v_exp_f32_e32 v165, v178
	v_add_f32_e32 v112, v112, v125
	v_add_f32_e32 v113, v113, v126
	v_exp_f32_e32 v178, v179
	v_add_f32_e32 v112, v112, v165
	v_add_f32_e32 v113, v113, v178
	v_exp_f32_e32 v176, v176
	v_add_f32_e32 v112, v112, v127
	v_add_f32_e32 v113, v113, v160
	v_exp_f32_e32 v177, v177
	v_add_f32_e32 v112, v112, v176
	v_add_f32_e32 v113, v113, v177
	v_exp_f32_e32 v174, v174
	v_add_f32_e32 v112, v112, v161
	v_add_f32_e32 v113, v113, v162
	v_exp_f32_e32 v175, v175
	v_add_f32_e32 v112, v112, v174
	v_add_f32_e32 v113, v113, v175
	v_exp_f32_e32 v172, v172
	v_add_f32_e32 v112, v112, v116
	v_add_f32_e32 v113, v113, v117
	v_exp_f32_e32 v173, v173
	v_add_f32_e32 v112, v112, v172
	v_add_f32_e32 v113, v113, v173
	v_exp_f32_e32 v170, v170
	v_add_f32_e32 v112, v112, v118
	v_add_f32_e32 v113, v113, v119
	v_exp_f32_e32 v171, v171
	v_add_f32_e32 v112, v112, v170
	v_add_f32_e32 v113, v113, v171
	v_exp_f32_e32 v168, v168
	v_add_f32_e32 v112, v112, v120
	v_add_f32_e32 v113, v113, v121
	v_exp_f32_e32 v169, v169
	v_exp_f32_e32 v166, v166
	v_exp_f32_e32 v167, v167
	v_add_f32_e32 v112, v112, v168
	v_add_f32_e32 v113, v113, v169
	s_nop 0
	v_add_f32_e32 v112, v112, v122
	v_add_f32_e32 v113, v113, v123
	s_nop 0
	v_add_f32_e32 v112, v112, v166
	v_add_f32_e32 v113, v113, v167
	s_nop 0
	v_add_f32_e32 v225, v112, v113
	v_cvt_pk_bf16_f32 v112, v115, v124
	v_cvt_pk_bf16_f32 v113, v125, v126
	v_cvt_pk_bf16_f32 v114, v127, v160
	v_cvt_pk_bf16_f32 v115, v161, v162
	v_cvt_pk_bf16_f32 v116, v116, v117
	s_nop 0
	v_mov_b32_e32 v226, v225
	s_nop 1
	v_permlane32_swap_b32_e32 v225, v226
	v_cvt_pk_bf16_f32 v117, v118, v119
	v_cvt_pk_bf16_f32 v118, v120, v121
	v_cvt_pk_bf16_f32 v119, v122, v123
	v_cvt_pk_bf16_f32 v120, v163, v164
	v_cvt_pk_bf16_f32 v121, v165, v178
	v_cvt_pk_bf16_f32 v122, v176, v177
	v_cvt_pk_bf16_f32 v123, v174, v175
	v_cvt_pk_bf16_f32 v124, v172, v173
	v_cvt_pk_bf16_f32 v125, v170, v171
	v_cvt_pk_bf16_f32 v126, v168, v169
	v_cvt_pk_bf16_f32 v127, v166, v167
	v_permlane32_swap_b32_e32 v112, v114
	v_permlane32_swap_b32_e32 v113, v115
	v_permlane32_swap_b32_e32 v116, v118
	v_permlane32_swap_b32_e32 v117, v119
	v_permlane32_swap_b32_e32 v120, v122
	v_permlane32_swap_b32_e32 v121, v123
	v_permlane32_swap_b32_e32 v124, v126
	v_permlane32_swap_b32_e32 v125, v127
	s_lshl_b32 s0, s36, 14
	v_add_u32_e32 v230, s0, v187
	ds_read_b64_tr_b16 v[160:161], v230 offset:0
	ds_read_b64_tr_b16 v[162:163], v230 offset:0x800
	ds_read_b64_tr_b16 v[164:165], v230 offset:0x1000
	ds_read_b64_tr_b16 v[166:167], v230 offset:0x1800
	ds_read_b64_tr_b16 v[168:169], v230 offset:0x2000
	ds_read_b64_tr_b16 v[170:171], v230 offset:0x2800
	ds_read_b64_tr_b16 v[172:173], v230 offset:0x3000
	ds_read_b64_tr_b16 v[174:175], v230 offset:0x3800
	s_setprio 1
	s_waitcnt lgkmcnt(6)
	v_mfma_f32_32x32x16_bf16 v[48:63], v[112:115], v[160:163], v[48:63]
	s_waitcnt lgkmcnt(4)
	v_mfma_f32_32x32x16_bf16 v[48:63], v[116:119], v[164:167], v[48:63]
	s_waitcnt lgkmcnt(2)
	v_mfma_f32_32x32x16_bf16 v[48:63], v[120:123], v[168:171], v[48:63]
	s_waitcnt lgkmcnt(0)
	v_mfma_f32_32x32x16_bf16 v[48:63], v[124:127], v[172:175], v[48:63]
	s_setprio 0
	v_max3_f32 v160, v80, v81, v82
	v_max3_f32 v161, v64, v65, v66
	v_max_f32_e32 v162, v79, v79
	v_max3_f32 v160, v160, v83, v84
	v_max3_f32 v161, v161, v67, v68
	v_max_f32_e32 v163, v95, v95
	v_max3_f32 v160, v160, v85, v86
	v_max3_f32 v161, v161, v69, v70
	v_max_f32_e32 v162, v163, v162
	v_max3_f32 v160, v160, v87, v88
	v_max3_f32 v161, v161, v71, v72
	s_nop 0
	v_max3_f32 v160, v160, v89, v90
	v_max3_f32 v161, v161, v73, v74
	s_nop 0
	v_max3_f32 v160, v160, v91, v92
	v_max3_f32 v161, v161, v75, v76
	s_nop 0
	v_max3_f32 v160, v160, v93, v94
	v_max3_f32 v161, v161, v77, v78
	s_nop 0
	v_max3_f32 v160, v160, v161, v162
	s_nop 0
	v_mov_b32_e32 v161, v160
	s_nop 1
	v_permlane32_swap_b32_e32 v160, v161
	v_max_f32_e32 v161, v161, v161
	v_max_f32_e32 v160, v160, v160
	v_max_f32_e32 v176, v160, v161
	ds_read_b64_tr_b16 v[160:161], v230 offset:0x200
	ds_read_b64_tr_b16 v[162:163], v230 offset:0xa00
	ds_read_b64_tr_b16 v[164:165], v230 offset:0x1200
	ds_read_b64_tr_b16 v[166:167], v230 offset:0x1a00
	ds_read_b64_tr_b16 v[168:169], v230 offset:0x2200
	ds_read_b64_tr_b16 v[170:171], v230 offset:0x2a00
	ds_read_b64_tr_b16 v[172:173], v230 offset:0x3200
	ds_read_b64_tr_b16 v[174:175], v230 offset:0x3a00
	s_setprio 1
	s_waitcnt lgkmcnt(6)
	v_mfma_f32_32x32x16_bf16 v[32:47], v[112:115], v[160:163], v[32:47]
	s_waitcnt lgkmcnt(4)
	v_mfma_f32_32x32x16_bf16 v[32:47], v[116:119], v[164:167], v[32:47]
	s_waitcnt lgkmcnt(2)
	v_mfma_f32_32x32x16_bf16 v[32:47], v[120:123], v[168:171], v[32:47]
	s_waitcnt lgkmcnt(0)
	v_mfma_f32_32x32x16_bf16 v[32:47], v[124:127], v[172:175], v[32:47]
	s_setprio 0
	v_sub_f32_e32 v160, v176, v227
	v_cmp_ge_f32_e32 vcc, s71, v160
	v_max_f32_e32 v160, v227, v227
	v_max_f32_e32 v160, v160, v176
	v_sub_f32_e32 v161, v227, v160
	v_mul_f32_e32 v161, 0x3e38aa3b, v161
	v_exp_f32_e32 v161, v161
	s_cmp_eq_u64 vcc, exec
	s_cselect_b64 vcc, -1, 0
	v_cndmask_b32_e32 v229, v160, v227, vcc
	v_cndmask_b32_e64 v228, v161, 1.0, vcc
	v_mul_f32_e32 v160, 0xbe38aa3b, v229
	v_fma_f32 v80, v80, v197, v160
	v_fma_f32 v81, v81, v197, v160
	v_fma_f32 v82, v82, v197, v160
	v_fma_f32 v83, v83, v197, v160
	v_fma_f32 v84, v84, v197, v160
	v_fma_f32 v85, v85, v197, v160
	v_fma_f32 v86, v86, v197, v160
	v_fma_f32 v87, v87, v197, v160
	v_fma_f32 v88, v88, v197, v160
	v_fma_f32 v89, v89, v197, v160
	v_fma_f32 v90, v90, v197, v160
	v_fma_f32 v91, v91, v197, v160
	v_fma_f32 v92, v92, v197, v160
	v_fma_f32 v93, v93, v197, v160
	v_fma_f32 v94, v94, v197, v160
	v_fma_f32 v95, v95, v197, v160
	v_fma_f32 v166, v64, v197, v160
	v_fma_f32 v167, v65, v197, v160
	v_fma_f32 v168, v66, v197, v160
	v_fma_f32 v169, v67, v197, v160
	v_fma_f32 v170, v68, v197, v160
	v_fma_f32 v171, v69, v197, v160
	v_fma_f32 v172, v70, v197, v160
	v_fma_f32 v173, v71, v197, v160
	v_fma_f32 v174, v72, v197, v160
	v_fma_f32 v175, v73, v197, v160
	v_fma_f32 v176, v74, v197, v160
	v_fma_f32 v177, v75, v197, v160
	v_fma_f32 v178, v76, v197, v160
	v_fma_f32 v179, v77, v197, v160
	v_fma_f32 v180, v78, v197, v160
	v_fma_f32 v181, v79, v197, v160
	ds_read_b64_tr_b16 v[64:65], v230 offset:0x400
	ds_read_b64_tr_b16 v[66:67], v230 offset:0xc00
	ds_read_b64_tr_b16 v[68:69], v230 offset:0x1400
	ds_read_b64_tr_b16 v[70:71], v230 offset:0x1c00
	ds_read_b64_tr_b16 v[72:73], v230 offset:0x2400
	ds_read_b64_tr_b16 v[74:75], v230 offset:0x2c00
	ds_read_b64_tr_b16 v[76:77], v230 offset:0x3400
	ds_read_b64_tr_b16 v[78:79], v230 offset:0x3c00
	s_setprio 1
	s_waitcnt lgkmcnt(6)
	v_mfma_f32_32x32x16_bf16 v[16:31], v[112:115], v[64:67], v[16:31]
	ds_read_b64_tr_b16 v[64:65], v230 offset:0x600
	ds_read_b64_tr_b16 v[66:67], v230 offset:0xe00
	s_waitcnt lgkmcnt(6)
	v_mfma_f32_32x32x16_bf16 v[16:31], v[116:119], v[68:71], v[16:31]
	ds_read_b64_tr_b16 v[68:69], v230 offset:0x1600
	ds_read_b64_tr_b16 v[70:71], v230 offset:0x1e00
	s_waitcnt lgkmcnt(6)
	v_mfma_f32_32x32x16_bf16 v[16:31], v[120:123], v[72:75], v[16:31]
	ds_read_b64_tr_b16 v[72:73], v230 offset:0x2600
	ds_read_b64_tr_b16 v[74:75], v230 offset:0x2e00
	s_waitcnt lgkmcnt(6)
	v_mfma_f32_32x32x16_bf16 v[16:31], v[124:127], v[76:79], v[16:31]
	ds_read_b64_tr_b16 v[76:77], v230 offset:0x3600
	ds_read_b64_tr_b16 v[78:79], v230 offset:0x3e00
	s_setprio 0
	s_setprio 0
	s_lshl_b32 s1, s36, 13
	v_lshl_add_u64 v[160:161], s[64:65], 0, v[154:155]
	s_add_i32 s1, s75, s1
	s_waitcnt vmcnt(0) lgkmcnt(0)
	s_barrier
	s_setprio 1
	v_mfma_f32_32x32x16_bf16 v[0:15], v[112:115], v[64:67], v[0:15]
	v_lshl_add_u64 v[232:233], v[160:161], 0, s[58:59]
	s_add_i32 m0, s1, 0xc000
	v_lshl_add_u64 v[162:163], s[64:65], 0, v[156:157]
	s_add_i32 s0, s75, s0
	global_load_lds_dwordx4 v[232:233], off
	v_mfma_f32_32x32x16_bf16 v[0:15], v[116:119], v[68:71], v[0:15]
	v_lshl_add_u64 v[232:233], v[162:163], 0, s[10:11]
	s_mov_b32 m0, s0
	v_lshl_add_u64 v[164:165], s[64:65], 0, v[158:159]
	global_load_lds_dwordx4 v[232:233], off
	v_mfma_f32_32x32x16_bf16 v[0:15], v[120:123], v[72:75], v[0:15]
	v_lshl_add_u64 v[232:233], v[164:165], 0, s[10:11]
	s_add_i32 m0, s0, 0x2000
	v_cmp_gt_f32_e32 vcc, 1.0, v228
	global_load_lds_dwordx4 v[232:233], off
	v_mfma_f32_32x32x16_bf16 v[0:15], v[124:127], v[76:79], v[0:15]
	s_setprio 0
	s_cbranch_vccz .LBB0_1054
	s_and_saveexec_b64 s[0:1], s[4:5]
	ds_write_b32 v223, v228 offset:128
	s_or_b64 exec, exec, s[0:1]
	s_waitcnt lgkmcnt(0)
	v_add_u32_e32 v76, s33, v188
	ds_read_b128 v[64:67], v76 offset:224
	ds_read_b128 v[68:71], v76 offset:192
	ds_read_b128 v[72:75], v76 offset:160
	ds_read_b128 v[76:79], v76 offset:128
	s_waitcnt lgkmcnt(0)
	v_pk_mul_f32 v[60:61], v[60:61], v[64:65]
	v_pk_mul_f32 v[56:57], v[56:57], v[68:69]
	v_pk_mul_f32 v[52:53], v[52:53], v[72:73]
	v_pk_mul_f32 v[62:63], v[62:63], v[66:67]
	v_pk_mul_f32 v[58:59], v[58:59], v[70:71]
	v_pk_mul_f32 v[54:55], v[54:55], v[74:75]
	v_pk_mul_f32 v[50:51], v[50:51], v[78:79]
	v_pk_mul_f32 v[48:49], v[48:49], v[76:77]
	v_pk_mul_f32 v[44:45], v[44:45], v[64:65]
	v_pk_mul_f32 v[40:41], v[40:41], v[68:69]
	v_pk_mul_f32 v[36:37], v[36:37], v[72:73]
	v_pk_mul_f32 v[46:47], v[46:47], v[66:67]
	v_pk_mul_f32 v[42:43], v[42:43], v[70:71]
	v_pk_mul_f32 v[38:39], v[38:39], v[74:75]
	v_pk_mul_f32 v[34:35], v[34:35], v[78:79]
	v_pk_mul_f32 v[32:33], v[32:33], v[76:77]
	v_pk_mul_f32 v[28:29], v[28:29], v[64:65]
	v_pk_mul_f32 v[24:25], v[24:25], v[68:69]
	v_pk_mul_f32 v[20:21], v[20:21], v[72:73]
	v_pk_mul_f32 v[30:31], v[30:31], v[66:67]
	v_pk_mul_f32 v[26:27], v[26:27], v[70:71]
	v_pk_mul_f32 v[22:23], v[22:23], v[74:75]
	v_pk_mul_f32 v[18:19], v[18:19], v[78:79]
	v_pk_mul_f32 v[16:17], v[16:17], v[76:77]
	v_pk_mul_f32 v[12:13], v[12:13], v[64:65]
	v_pk_mul_f32 v[8:9], v[8:9], v[68:69]
	v_pk_mul_f32 v[4:5], v[4:5], v[72:73]
	v_pk_mul_f32 v[14:15], v[14:15], v[66:67]
	v_pk_mul_f32 v[10:11], v[10:11], v[70:71]
	v_pk_mul_f32 v[6:7], v[6:7], v[74:75]
	v_pk_mul_f32 v[2:3], v[2:3], v[78:79]
	v_pk_mul_f32 v[0:1], v[0:1], v[76:77]
.LBB0_1054:
	v_exp_f32_e32 v227, v88
	v_exp_f32_e32 v232, v89
	s_add_i32 s0, s76, 1
	s_cmp_lg_u32 s76, 2
	s_cselect_b32 s36, s0, 0
	v_exp_f32_e32 v120, v80
	v_exp_f32_e32 v121, v81
	v_exp_f32_e32 v122, v82
	v_exp_f32_e32 v123, v83
	v_exp_f32_e32 v124, v84
	v_exp_f32_e32 v125, v85
	v_exp_f32_e32 v126, v86
	v_exp_f32_e32 v127, v87
	v_exp_f32_e32 v233, v90
	v_exp_f32_e32 v234, v91
	v_exp_f32_e32 v235, v92
	v_exp_f32_e32 v236, v93
	v_exp_f32_e32 v237, v94
	v_exp_f32_e32 v238, v95
	s_setprio 1
	v_lshl_add_u32 v230, s36, 13, v190
	v_add_u32_e32 v68, v230, v191
	ds_read_b128 v[64:67], v68 offset:49152
	ds_read_b128 v[68:71], v68 offset:53248
	v_add_u32_e32 v116, v230, v192
	ds_read_b128 v[112:115], v116 offset:49152
	ds_read_b128 v[116:119], v116 offset:53248
	s_waitcnt lgkmcnt(2)
	v_mfma_f32_32x32x16_bf16 v[80:95], v[64:67], v[108:111], 0
	v_mfma_f32_32x32x16_bf16 v[64:79], v[68:71], v[108:111], 0
	s_waitcnt lgkmcnt(0)
	v_mfma_f32_32x32x16_bf16 v[80:95], v[112:115], v[104:107], v[80:95]
	v_add_u32_e32 v112, v230, v193
	ds_read_b128 v[112:115], v112 offset:49152
	v_mfma_f32_32x32x16_bf16 v[64:79], v[116:119], v[104:107], v[64:79]
	v_add_u32_e32 v116, v230, v193
	ds_read_b128 v[116:119], v116 offset:53248
	s_waitcnt lgkmcnt(1)
	v_mfma_f32_32x32x16_bf16 v[80:95], v[112:115], v[100:103], v[80:95]
	v_add_u32_e32 v112, v230, v194
	ds_read_b128 v[112:115], v112 offset:49152
	s_waitcnt lgkmcnt(1)
	v_mfma_f32_32x32x16_bf16 v[64:79], v[116:119], v[100:103], v[64:79]
	v_add_u32_e32 v116, v230, v194
	ds_read_b128 v[116:119], v116 offset:53248
	s_waitcnt lgkmcnt(1)
	v_mfma_f32_32x32x16_bf16 v[80:95], v[112:115], v[96:99], v[80:95]
	s_waitcnt lgkmcnt(0)
	v_mfma_f32_32x32x16_bf16 v[64:79], v[116:119], v[96:99], v[64:79]
	s_setprio 0
	v_exp_f32_e32 v166, v166
	v_exp_f32_e32 v167, v167
	v_add_f32_e32 v112, v120, v166
	v_add_f32_e32 v113, v121, v167
	v_exp_f32_e32 v168, v168
	v_add_f32_e32 v112, v112, v122
	v_add_f32_e32 v113, v113, v123
	v_exp_f32_e32 v169, v169
	v_add_f32_e32 v112, v112, v168
	v_add_f32_e32 v113, v113, v169
	v_exp_f32_e32 v170, v170
	v_add_f32_e32 v112, v112, v124
	v_add_f32_e32 v113, v113, v125
	v_exp_f32_e32 v171, v171
	v_add_f32_e32 v112, v112, v170
	v_add_f32_e32 v113, v113, v171
	v_exp_f32_e32 v172, v172
	v_add_f32_e32 v112, v112, v126
	v_add_f32_e32 v113, v113, v127
	v_exp_f32_e32 v173, v173
	v_add_f32_e32 v112, v112, v172
	v_add_f32_e32 v113, v113, v173
	v_exp_f32_e32 v174, v174
	v_add_f32_e32 v112, v112, v227
	v_add_f32_e32 v113, v113, v232
	v_exp_f32_e32 v175, v175
	v_add_f32_e32 v112, v112, v174
	v_add_f32_e32 v113, v113, v175
	v_exp_f32_e32 v176, v176
	v_add_f32_e32 v112, v112, v233
	v_add_f32_e32 v113, v113, v234
	v_exp_f32_e32 v177, v177
	v_add_f32_e32 v112, v112, v176
	v_add_f32_e32 v113, v113, v177
	v_exp_f32_e32 v178, v178
	v_add_f32_e32 v112, v112, v235
	v_add_f32_e32 v113, v113, v236
	v_exp_f32_e32 v179, v179
	v_exp_f32_e32 v180, v180
	v_exp_f32_e32 v181, v181
	v_add_f32_e32 v112, v112, v178
	v_add_f32_e32 v113, v113, v179
	s_nop 0
	v_add_f32_e32 v112, v112, v237
	v_add_f32_e32 v113, v113, v238
	s_nop 0
	v_add_f32_e32 v112, v112, v180
	v_add_f32_e32 v113, v113, v181
	s_nop 0
	v_add_f32_e32 v230, v112, v113
	v_cvt_pk_bf16_f32 v112, v120, v121
	v_cvt_pk_bf16_f32 v113, v122, v123
	v_cvt_pk_bf16_f32 v114, v124, v125
	v_cvt_pk_bf16_f32 v115, v126, v127
	v_cvt_pk_bf16_f32 v116, v227, v232
	s_nop 0
	v_mov_b32_e32 v231, v230
	s_nop 1
	v_permlane32_swap_b32_e32 v230, v231
	v_cvt_pk_bf16_f32 v117, v233, v234
	v_cvt_pk_bf16_f32 v118, v235, v236
	v_cvt_pk_bf16_f32 v119, v237, v238
	v_cvt_pk_bf16_f32 v120, v166, v167
	v_cvt_pk_bf16_f32 v121, v168, v169
	v_cvt_pk_bf16_f32 v122, v170, v171
	v_cvt_pk_bf16_f32 v123, v172, v173
	v_cvt_pk_bf16_f32 v124, v174, v175
	v_cvt_pk_bf16_f32 v125, v176, v177
	v_cvt_pk_bf16_f32 v126, v178, v179
	v_cvt_pk_bf16_f32 v127, v180, v181
	v_permlane32_swap_b32_e32 v112, v114
	v_permlane32_swap_b32_e32 v113, v115
	v_permlane32_swap_b32_e32 v116, v118
	v_permlane32_swap_b32_e32 v117, v119
	v_permlane32_swap_b32_e32 v120, v122
	v_permlane32_swap_b32_e32 v121, v123
	v_permlane32_swap_b32_e32 v124, v126
	v_permlane32_swap_b32_e32 v125, v127
	s_lshl_b32 s41, s76, 14
	v_add_u32_e32 v233, s41, v187
	ds_read_b64_tr_b16 v[166:167], v233 offset:0
	ds_read_b64_tr_b16 v[168:169], v233 offset:0x800
	ds_read_b64_tr_b16 v[170:171], v233 offset:0x1000
	ds_read_b64_tr_b16 v[172:173], v233 offset:0x1800
	ds_read_b64_tr_b16 v[174:175], v233 offset:0x2000
	ds_read_b64_tr_b16 v[176:177], v233 offset:0x2800
	ds_read_b64_tr_b16 v[178:179], v233 offset:0x3000
	ds_read_b64_tr_b16 v[180:181], v233 offset:0x3800
	s_setprio 1
	s_waitcnt lgkmcnt(6)
	v_mfma_f32_32x32x16_bf16 v[48:63], v[112:115], v[166:169], v[48:63]
	s_waitcnt lgkmcnt(4)
	v_mfma_f32_32x32x16_bf16 v[48:63], v[116:119], v[170:173], v[48:63]
	s_waitcnt lgkmcnt(2)
	v_mfma_f32_32x32x16_bf16 v[48:63], v[120:123], v[174:177], v[48:63]
	s_waitcnt lgkmcnt(0)
	v_mfma_f32_32x32x16_bf16 v[48:63], v[124:127], v[178:181], v[48:63]
	s_setprio 0
	v_max3_f32 v166, v80, v81, v82
	v_max3_f32 v167, v64, v65, v66
	v_max_f32_e32 v168, v79, v79
	v_max3_f32 v166, v166, v83, v84
	v_max3_f32 v167, v167, v67, v68
	v_max_f32_e32 v169, v95, v95
	v_max3_f32 v166, v166, v85, v86
	v_max3_f32 v167, v167, v69, v70
	v_max_f32_e32 v168, v169, v168
	v_max3_f32 v166, v166, v87, v88
	v_max3_f32 v167, v167, v71, v72
	s_nop 0
	v_max3_f32 v166, v166, v89, v90
	v_max3_f32 v167, v167, v73, v74
	s_nop 0
	v_max3_f32 v166, v166, v91, v92
	v_max3_f32 v167, v167, v75, v76
	s_nop 0
	v_max3_f32 v166, v166, v93, v94
	v_max3_f32 v167, v167, v77, v78
	s_nop 0
	v_max3_f32 v166, v166, v167, v168
	s_nop 0
	v_mov_b32_e32 v167, v166
	s_nop 1
	v_permlane32_swap_b32_e32 v166, v167
	v_max_f32_e32 v167, v167, v167
	v_max_f32_e32 v166, v166, v166
	v_max_f32_e32 v227, v166, v167
	ds_read_b64_tr_b16 v[166:167], v233 offset:0x200
	ds_read_b64_tr_b16 v[168:169], v233 offset:0xa00
	ds_read_b64_tr_b16 v[170:171], v233 offset:0x1200
	ds_read_b64_tr_b16 v[172:173], v233 offset:0x1a00
	ds_read_b64_tr_b16 v[174:175], v233 offset:0x2200
	ds_read_b64_tr_b16 v[176:177], v233 offset:0x2a00
	ds_read_b64_tr_b16 v[178:179], v233 offset:0x3200
	ds_read_b64_tr_b16 v[180:181], v233 offset:0x3a00
	s_setprio 1
	s_waitcnt lgkmcnt(6)
	v_mfma_f32_32x32x16_bf16 v[32:47], v[112:115], v[166:169], v[32:47]
	s_waitcnt lgkmcnt(4)
	v_mfma_f32_32x32x16_bf16 v[32:47], v[116:119], v[170:173], v[32:47]
	s_waitcnt lgkmcnt(2)
	v_mfma_f32_32x32x16_bf16 v[32:47], v[120:123], v[174:177], v[32:47]
	s_waitcnt lgkmcnt(0)
	v_mfma_f32_32x32x16_bf16 v[32:47], v[124:127], v[178:181], v[32:47]
	s_setprio 0
	v_sub_f32_e32 v166, v227, v229
	v_cmp_ge_f32_e32 vcc, s71, v166
	s_cmp_eq_u64 vcc, exec
	v_max_f32_e32 v166, v229, v229
	v_max_f32_e32 v232, v166, v227
	s_cselect_b64 s[0:1], -1, 0
	v_cndmask_b32_e64 v227, v232, v229, s[0:1]
	v_mul_f32_e32 v167, 0xbe38aa3b, v227
	v_fma_f32 v80, v80, v197, v167
	v_fma_f32 v81, v81, v197, v167
	v_fma_f32 v82, v82, v197, v167
	v_fma_f32 v83, v83, v197, v167
	v_fma_f32 v84, v84, v197, v167
	v_fma_f32 v85, v85, v197, v167
	v_fma_f32 v86, v86, v197, v167
	v_fma_f32 v87, v87, v197, v167
	v_fma_f32 v88, v88, v197, v167
	v_fma_f32 v89, v89, v197, v167
	v_fma_f32 v90, v90, v197, v167
	v_fma_f32 v91, v91, v197, v167
	v_fma_f32 v92, v92, v197, v167
	v_fma_f32 v93, v93, v197, v167
	v_fma_f32 v94, v94, v197, v167
	v_fma_f32 v95, v95, v197, v167
	v_fma_f32 v180, v64, v197, v167
	v_fma_f32 v181, v65, v197, v167
	v_fma_f32 v178, v66, v197, v167
	v_fma_f32 v179, v67, v197, v167
	v_fma_f32 v176, v68, v197, v167
	v_fma_f32 v177, v69, v197, v167
	v_fma_f32 v174, v70, v197, v167
	v_fma_f32 v175, v71, v197, v167
	v_fma_f32 v172, v72, v197, v167
	v_fma_f32 v173, v73, v197, v167
	v_fma_f32 v170, v74, v197, v167
	v_fma_f32 v171, v75, v197, v167
	v_fma_f32 v168, v76, v197, v167
	v_fma_f32 v169, v77, v197, v167
	v_fma_f32 v166, v78, v197, v167
	v_fma_f32 v167, v79, v197, v167
	ds_read_b64_tr_b16 v[64:65], v233 offset:0x400
	ds_read_b64_tr_b16 v[66:67], v233 offset:0xc00
	ds_read_b64_tr_b16 v[68:69], v233 offset:0x1400
	ds_read_b64_tr_b16 v[70:71], v233 offset:0x1c00
	ds_read_b64_tr_b16 v[72:73], v233 offset:0x2400
	ds_read_b64_tr_b16 v[74:75], v233 offset:0x2c00
	ds_read_b64_tr_b16 v[76:77], v233 offset:0x3400
	ds_read_b64_tr_b16 v[78:79], v233 offset:0x3c00
	s_setprio 1
	s_waitcnt lgkmcnt(6)
	v_mfma_f32_32x32x16_bf16 v[16:31], v[112:115], v[64:67], v[16:31]
	ds_read_b64_tr_b16 v[64:65], v233 offset:0x600
	ds_read_b64_tr_b16 v[66:67], v233 offset:0xe00
	s_waitcnt lgkmcnt(6)
	v_mfma_f32_32x32x16_bf16 v[16:31], v[116:119], v[68:71], v[16:31]
	ds_read_b64_tr_b16 v[68:69], v233 offset:0x1600
	ds_read_b64_tr_b16 v[70:71], v233 offset:0x1e00
	s_waitcnt lgkmcnt(6)
	v_mfma_f32_32x32x16_bf16 v[16:31], v[120:123], v[72:75], v[16:31]
	ds_read_b64_tr_b16 v[72:73], v233 offset:0x2600
	ds_read_b64_tr_b16 v[74:75], v233 offset:0x2e00
	s_waitcnt lgkmcnt(6)
	v_mfma_f32_32x32x16_bf16 v[16:31], v[124:127], v[76:79], v[16:31]
	ds_read_b64_tr_b16 v[76:77], v233 offset:0x3600
	ds_read_b64_tr_b16 v[78:79], v233 offset:0x3e00
	s_setprio 0
	s_setprio 0
	s_waitcnt vmcnt(0) lgkmcnt(0)
	s_barrier
	s_cmp_gt_u32 s37, 28
	s_cselect_b64 s[38:39], -1, 0
	s_and_b64 vcc, exec, s[38:39]
	s_cbranch_vccnz .Lpv3_skip_b
	s_add_i32 s40, s40, s74
	s_setprio 1
	v_mfma_f32_32x32x16_bf16 v[0:15], v[112:115], v[64:67], v[0:15]
	s_add_i32 m0, s40, 0xc000
	s_add_i32 s40, s75, s41
	v_lshl_add_u64 v[64:65], v[160:161], 0, s[60:61]
	global_load_lds_dwordx4 v[64:65], off
	v_mfma_f32_32x32x16_bf16 v[0:15], v[116:119], v[68:71], v[0:15]
	v_lshl_add_u64 v[64:65], v[162:163], 0, s[34:35]
	s_mov_b32 m0, s40
	s_nop 0
	global_load_lds_dwordx4 v[64:65], off
	v_mfma_f32_32x32x16_bf16 v[0:15], v[120:123], v[72:75], v[0:15]
	v_lshl_add_u64 v[64:65], v[164:165], 0, s[34:35]
	s_add_i32 m0, s40, 0x2000
	s_nop 0
	global_load_lds_dwordx4 v[64:65], off
	v_mfma_f32_32x32x16_bf16 v[0:15], v[124:127], v[76:79], v[0:15]
	s_setprio 0
	s_branch .LBB0_1056
